# v54 + P9 wave-pair rebalance: waves 4-7 skip their last slot, waves 0-3 re-enter the prologue as gw+4 and process it (9/7 slots instead of 8/8)
# baseline (speedup 1.0000x reference)
; #define LAS __attribute__((address_space(3)))
; __device__ __forceinline__ void s5_out_phase(LAS unsigned char* lds, const bf16_t* UZ, const unsigned char* ws, const float* dskip, bf16_t* YG) {
;     const int lane = threadIdx.x & 63, wave = __builtin_amdgcn_readfirstlane(threadIdx.x >> 6);
;     LAS unsigned char* wl = lds + wave * S5_WAVE_LDS;
;     const int gw = blockIdx.x * 8 + wave, NGW = gridDim.x * 8;
;     const float* E = (const float*)(ws + WS_E);
;     const int g = gw & 63, fr = lane & 15, fq = lane >> 4;
;     const f32x4 dsk = *(const f32x4*)(dskip + 16 * g + 4 * fq);
;     bf16x4 Bf[2][8]; bf16x8 Cf[2][4]; f32x4 ap[2];
; #pragma unroll
;     for (int dir = 0; dir < 2; ++dir) {
;         const int pair = dir * 64 + g;
;         const bf16_t* Bb = (const bf16_t*)(ws + WS_BB) + (size_t)pair * 128 * 16;
;         const bf16_t* Cm = (const bf16_t*)(ws + WS_CM) + (size_t)pair * 16 * 128;
; #pragma unroll
;         for (int nt = 0; nt < 8; ++nt) Bf[dir][nt] = *(const bf16x4*)(Bb + (16 * nt + fr) * 16 + 4 * fq);
; #pragma unroll
;         for (int ks = 0; ks < 4; ++ks) Cf[dir][ks] = *(const bf16x8*)(Cm + fr * 128 + 8 * fq + 32 * ks);
;         ap[dir] = ((const f32x4*)(ws + WS_APOW))[pair * 64 + lane];
;     }
;     const int wofs = (fr >> 1) * 80 + (fr & 1) * 32 + 8 * fq;
;     const int sstep = NGW >> 6;
;     const float* QE = (const float*)(ws + WS_QE);
;     bf16x4 Un[4]; f32x2 rp[2], rq[2][3];
;     ...
;     { const int slot = gw >> 6, b = slot >> 6, tt = slot & 63;
;       load_uf(Un, UZ, b * SEQ + 64 * tt, g, lane);
;       S5_LOADRAW(b, tt); }
.LBB0_752:
	s_cmp_lt_i32 s68, 10
	s_cselect_b64 s[0:1], -1, 0
	s_cmp_gt_i32 s69, 9
	s_cselect_b64 s[2:3], -1, 0
	s_and_b64 s[0:1], s[0:1], s[2:3]
	s_andn2_b64 vcc, exec, s[0:1]
	s_cbranch_vccnz .LBB0_762
	v_readfirstlane_b32 s2, v192
	s_lshr_b32 s8, s2, 6
	s_lshl_b32 s2, s12, 3
	s_add_i32 s24, s8, s2
	s_mov_b64 s[96:97], s[20:21]
	s_mov_b32 s100, 0
	s_movk_i32 s101, 0xff
	s_cmp_lt_u32 s8, 4
	s_cbranch_scc1 .Lp9_entry
	s_movk_i32 s101, 0xdf
.Lp9_entry:
	s_ashr_i32 s5, s24, 6
	s_cmp_gt_i32 s5, s101
	s_cbranch_scc1 .LBB0_762
	s_waitcnt vmcnt(0)
	v_lshrrev_b32_e32 v0, 1, v192
	v_and_b32_e32 v46, 24, v0
	v_mov_b32_e32 v47, 0
	v_and_b32_e32 v182, 15, v192
	v_lshl_add_u64 v[0:1], s[30:31], 0, v[46:47]
	s_mov_b64 s[22:23], 0x100000
	v_lshl_add_u64 v[16:17], v[0:1], 0, s[22:23]
	v_lshlrev_b32_e32 v0, 8, v182
	v_mov_b32_e32 v1, v47
	v_lshl_add_u64 v[0:1], s[30:31], 0, v[0:1]
	v_and_b32_e32 v44, 48, v192
	v_mov_b32_e32 v45, v47
	s_lshl_b32 s4, s14, 3
	s_and_b32 s9, s24, 63
	v_lshl_add_u64 v[0:1], v[0:1], 0, v[44:45]
	s_mov_b64 s[22:23], 0x180000
	v_lshl_add_u64 v[20:21], v[0:1], 0, s[22:23]
	s_add_u32 s22, s30, 0x80000
	s_mov_b32 s3, 0
	s_addc_u32 s23, s31, 0
	s_lshl_b32 s2, s9, 12
	v_lshl_add_u64 v[0:1], v[16:17], 0, s[2:3]
	v_lshlrev_b32_e32 v18, 5, v182
	v_mov_b32_e32 v19, v47
	s_or_b32 s36, s9, 64
	v_and_b32_e32 v56, 63, v192
	v_lshl_add_u64 v[0:1], v[0:1], 0, v[18:19]
	v_lshl_add_u64 v[22:23], v[20:21], 0, s[2:3]
	s_lshl_b32 s25, s9, 6
	s_lshl_b32 s2, s36, 12
	global_load_dwordx2 v[60:61], v[0:1], off
	global_load_dwordx2 v[62:63], v[0:1], off offset:512
	global_load_dwordx2 v[64:65], v[0:1], off offset:1024
	global_load_dwordx2 v[66:67], v[0:1], off offset:1536
	global_load_dwordx2 v[68:69], v[0:1], off offset:2048
	global_load_dwordx2 v[70:71], v[0:1], off offset:2560
	global_load_dwordx2 v[72:73], v[0:1], off offset:3072
	global_load_dwordx2 v[74:75], v[0:1], off offset:3584
	s_nop 0
	global_load_dwordx4 v[0:3], v[22:23], off
	global_load_dwordx4 v[4:7], v[22:23], off offset:64
	global_load_dwordx4 v[8:11], v[22:23], off offset:128
	global_load_dwordx4 v[12:15], v[22:23], off offset:192
	v_or_b32_e32 v22, s25, v56
	v_lshl_add_u64 v[16:17], v[16:17], 0, s[2:3]
	v_lshlrev_b32_e32 v24, 4, v22
	v_lshl_add_u64 v[22:23], v[16:17], 0, v[18:19]
	v_lshl_add_u64 v[36:37], v[20:21], 0, s[2:3]
	global_load_dwordx4 v[16:19], v24, s[22:23]
	global_load_dwordx2 v[76:77], v[22:23], off
	global_load_dwordx2 v[78:79], v[22:23], off offset:512
	global_load_dwordx2 v[80:81], v[22:23], off offset:1024
	global_load_dwordx2 v[82:83], v[22:23], off offset:1536
	global_load_dwordx2 v[84:85], v[22:23], off offset:2048
	global_load_dwordx2 v[86:87], v[22:23], off offset:2560
	global_load_dwordx2 v[88:89], v[22:23], off offset:3072
	global_load_dwordx2 v[90:91], v[22:23], off offset:3584
	s_nop 0
	global_load_dwordx4 v[20:23], v[36:37], off
	global_load_dwordx4 v[24:27], v[36:37], off offset:64
	global_load_dwordx4 v[28:31], v[36:37], off offset:128
	global_load_dwordx4 v[32:35], v[36:37], off offset:192
	v_lshlrev_b32_e32 v36, 4, v56
	v_lshl_or_b32 v36, s36, 10, v36
	s_add_u32 s2, s30, 0xc200000
	global_load_dwordx4 v[36:39], v36, s[22:23]
	s_addc_u32 s3, s31, 0
	s_lshl_b32 s22, s9, 5
	s_add_u32 s36, s18, s22
	s_addc_u32 s37, s19, 0
	v_lshlrev_b32_e32 v48, 2, v56
	v_mov_b32_e32 v49, v47
	v_lshl_add_u64 v[92:93], s[36:37], 0, v[46:47]
	v_lshl_add_u64 v[40:41], s[30:31], 0, v[48:49]
	s_mov_b64 s[36:37], 0x1700000
	v_lshl_add_u64 v[94:95], v[40:41], 0, s[36:37]
	s_ashr_i32 s36, s24, 5
	s_and_b32 s36, s36, 0xffffff80
	s_or_b32 s40, s9, s36
	s_mulk_i32 s8, 0x4a00
	s_or_b32 s38, s40, 64
	s_bfe_i32 s23, s14, 0x1a0003
	s_add_i32 s8, s8, 0
	s_mul_i32 s36, s38, 0x600
	s_mul_hi_i32 s37, s38, 0x600
	s_add_u32 s36, s2, s36
	s_addc_u32 s37, s3, s37
	s_bfe_u32 s42, s24, 0x60006
	s_mul_hi_i32 s39, s38, 0x44
	s_mulk_i32 s38, 0x44
	s_sub_i32 s41, 0x43, s42
	s_add_u32 s38, s38, s41
	s_addc_u32 s39, s39, 0
	s_lshl_b64 s[38:39], s[38:39], 9
	v_lshl_add_u64 v[40:41], v[94:95], 0, s[38:39]
	s_mul_i32 s38, s40, 0x600
	s_mul_hi_i32 s39, s40, 0x600
	s_add_u32 s38, s2, s38
	s_addc_u32 s39, s3, s39
	s_mul_hi_i32 s41, s40, 0x44
	s_mulk_i32 s40, 0x44
	s_add_i32 s43, s42, 4
	s_add_u32 s40, s40, s43
	s_addc_u32 s41, s41, 0
	s_lshl_b64 s[40:41], s[40:41], 9
	v_lshl_add_u64 v[42:43], v[94:95], 0, s[40:41]
	s_lshl_b32 s40, s42, 6
	s_and_b32 s24, s24, 0xfffff000
	s_or_b32 s24, s40, s24
	global_load_dword v183, v48, s[38:39] offset:1024
	global_load_dword v184, v48, s[38:39] offset:1280
	global_load_dword v96, v48, s[38:39] offset:512
	global_load_dword v97, v48, s[38:39] offset:768
	global_load_dword v99, v48, s[38:39] offset:256
	global_load_dword v106, v[40:41], off
	global_load_dword v107, v[40:41], off offset:256
	global_load_dword v100, v[42:43], off
	v_or_b32_e32 v40, s24, v182
	v_or_b32_e32 v50, 48, v40
	v_or_b32_e32 v52, 32, v40
	v_or_b32_e32 v54, 16, v40
	v_ashrrev_i32_e32 v51, 31, v50
	v_ashrrev_i32_e32 v53, 31, v52
	v_ashrrev_i32_e32 v55, 31, v54
	v_ashrrev_i32_e32 v41, 31, v40
	v_lshlrev_b64 v[50:51], 12, v[50:51]
	v_lshlrev_b64 v[52:53], 12, v[52:53]
	v_lshlrev_b64 v[54:55], 12, v[54:55]
	v_lshlrev_b64 v[40:41], 12, v[40:41]
	v_lshl_add_u64 v[50:51], v[92:93], 0, v[50:51]
	v_lshl_add_u64 v[52:53], v[92:93], 0, v[52:53]
	v_lshl_add_u64 v[54:55], v[92:93], 0, v[54:55]
	global_load_dword v101, v[42:43], off offset:256
	global_load_dwordx2 v[116:117], v[50:51], off
	global_load_dwordx2 v[168:169], v[52:53], off
	global_load_dwordx2 v[170:171], v[54:55], off
	v_lshl_add_u64 v[40:41], v[92:93], 0, v[40:41]
	global_load_dword v185, v48, s[36:37] offset:1024
	global_load_dword v186, v48, s[36:37] offset:1280
	global_load_dword v140, v48, s[36:37] offset:512
	global_load_dword v98, v48, s[38:39]
	global_load_dword v141, v48, s[36:37] offset:768
	global_load_dword v144, v48, s[36:37]
	global_load_dword v145, v48, s[36:37] offset:256
	global_load_dwordx2 v[172:173], v[40:41], off
	v_bfe_u32 v40, v192, 1, 3
	v_lshlrev_b32_e32 v41, 5, v192
	s_add_u32 s20, s20, s25
	v_mul_u32_u24_e32 v40, 0x50, v40
	v_and_b32_e32 v41, 32, v41
	s_addc_u32 s21, s21, 0
	v_add3_u32 v45, v40, v41, v46
	global_load_dwordx4 v[40:43], v44, s[20:21]
	s_waitcnt vmcnt(34)
; __device__ __forceinline__ f32x2 s5_carry(const f32x2 pre, const f32x2 (&qe)[3], const f32x4 ap, int c) {
;     ...
;     float A1r = ap.z, A1i = ap.w;
;     float A2r = A1r, A2i = A1i; cmul(A2r, A2i, A1r, A1i);
;     float A4r = A2r, A4i = A2i; cmul(A4r, A4i, A2r, A2i);
;     float A8r = A4r, A8i = A4i; cmul(A8r, A8i, A4r, A4i);
;     float A16r = A8r, A16i = A8i; cmul(A16r, A16i, A8r, A8i);
;     float A17r = A16r, A17i = A16i; cmul(A17r, A17i, A1r, A1i);
; __device__ __forceinline__ void s5_out_phase(LAS unsigned char* lds, const bf16_t* UZ, const unsigned char* ws, const float* dskip, bf16_t* YG) {
;     ...
;     const int wofs = (fr >> 1) * 80 + (fr & 1) * 32 + 8 * fq;
;     const int sstep = NGW >> 6;
;     const float* QE = (const float*)(ws + WS_QE);
;     bf16x4 Un[4]; f32x2 rp[2], rq[2][3];
;     ...
;     { const int slot = gw >> 6, b = slot >> 6, tt = slot & 63;
;       load_uf(Un, UZ, b * SEQ + 64 * tt, g, lane);
;       S5_LOADRAW(b, tt); }
;     for (int slot = gw >> 6; slot < 256; slot += sstep) {
;         const int b = slot >> 6, tt = slot & 63, rowbase = b * SEQ + 64 * tt;
;         bf16x4 Uf[4];
; #pragma unroll
;         for (int m = 0; m < 4; ++m) Uf[m] = Un[m];
;         const f32x2 cF_ = s5_carry(rp[0], rq[0], ap[0], 4 + tt), cB_ = s5_carry(rp[1], rq[1], ap[1], 4 + 63 - tt);
;         float xfr = cF_.x, xfi = cF_.y, xbr = cB_.x, xbi = cB_.y;
;         if (slot + sstep < 256) { const int ns = slot + sstep, nb = ns >> 6, ntt = ns & 63;
;             load_uf(Un, UZ, nb * SEQ + 64 * ntt, g, lane);
;             S5_LOADRAW(nb, ntt); }
	v_mov_b32_e32 v50, v19
	v_pk_mul_f32 v[50:51], v[50:51], v[18:19] op_sel_hi:[0,1]
	v_pk_fma_f32 v[102:103], v[18:19], v[18:19], v[50:51] op_sel:[0,1,0] op_sel_hi:[0,0,1]
	v_pk_fma_f32 v[104:105], v[18:19], v[18:19], v[50:51] op_sel:[0,1,0] op_sel_hi:[0,0,1] neg_lo:[0,0,1] neg_hi:[0,0,1]
	v_pk_mov_b32 v[52:53], v[104:105], v[102:103] op_sel:[1,0]
	v_mov_b32_e32 v50, v102
	v_mov_b32_e32 v51, v105
	v_pk_mul_f32 v[52:53], v[102:103], v[52:53] op_sel_hi:[0,1]
	v_pk_fma_f32 v[108:109], v[50:51], v[104:105], v[52:53] op_sel:[0,1,0]
	v_pk_fma_f32 v[110:111], v[50:51], v[104:105], v[52:53] op_sel:[0,1,0] neg_lo:[0,0,1] neg_hi:[0,0,1]
	v_mov_b32_e32 v50, v108
	v_pk_mov_b32 v[52:53], v[110:111], v[108:109] op_sel:[1,0]
	v_mov_b32_e32 v51, v111
	v_pk_mul_f32 v[52:53], v[108:109], v[52:53] op_sel_hi:[0,1]
	v_pk_fma_f32 v[112:113], v[50:51], v[110:111], v[52:53] op_sel:[0,1,0]
	v_pk_fma_f32 v[114:115], v[50:51], v[110:111], v[52:53] op_sel:[0,1,0] neg_lo:[0,0,1] neg_hi:[0,0,1]
	s_waitcnt vmcnt(21)
	v_mov_b32_e32 v52, v39
	v_pk_mul_f32 v[52:53], v[52:53], v[38:39] op_sel_hi:[0,1]
	v_pk_fma_f32 v[126:127], v[38:39], v[38:39], v[52:53] op_sel:[0,1,0] op_sel_hi:[0,0,1]
	v_pk_fma_f32 v[128:129], v[38:39], v[38:39], v[52:53] op_sel:[0,1,0] op_sel_hi:[0,0,1] neg_lo:[0,0,1] neg_hi:[0,0,1]
	v_pk_mov_b32 v[54:55], v[128:129], v[126:127] op_sel:[1,0]
	v_mov_b32_e32 v52, v126
	v_mov_b32_e32 v53, v129
	v_pk_mul_f32 v[54:55], v[126:127], v[54:55] op_sel_hi:[0,1]
	v_pk_fma_f32 v[130:131], v[52:53], v[128:129], v[54:55] op_sel:[0,1,0]
	v_pk_fma_f32 v[132:133], v[52:53], v[128:129], v[54:55] op_sel:[0,1,0] neg_lo:[0,0,1] neg_hi:[0,0,1]
	v_mov_b32_e32 v52, v130
	v_pk_mov_b32 v[54:55], v[132:133], v[130:131] op_sel:[1,0]
	v_mov_b32_e32 v53, v133
	v_pk_mul_f32 v[54:55], v[130:131], v[54:55] op_sel_hi:[0,1]
	v_pk_fma_f32 v[134:135], v[52:53], v[132:133], v[54:55] op_sel:[0,1,0]
	v_pk_fma_f32 v[136:137], v[52:53], v[132:133], v[54:55] op_sel:[0,1,0] neg_lo:[0,0,1] neg_hi:[0,0,1]
	v_mov_b32_e32 v113, v115
	v_mul_f32_e32 v50, v115, v115
	v_mov_b32_e32 v135, v137
	v_mul_f32_e32 v52, v137, v137
	v_pk_fma_f32 v[118:119], v[112:113], v[112:113], v[50:51] op_sel_hi:[1,1,0] neg_lo:[1,0,0] neg_hi:[1,0,0]
	v_pk_mul_f32 v[50:51], v[112:113], v[114:115] op_sel:[0,1] op_sel_hi:[1,0]
	v_pk_fma_f32 v[138:139], v[134:135], v[134:135], v[52:53] op_sel_hi:[1,1,0] neg_lo:[1,0,0] neg_hi:[1,0,0]
	v_pk_mul_f32 v[52:53], v[134:135], v[136:137] op_sel:[0,1] op_sel_hi:[1,0]
	v_pk_add_f32 v[120:121], v[50:51], v[50:51]
	v_pk_add_f32 v[142:143], v[52:53], v[52:53]
	s_movk_i32 s20, 0x110
	v_mov_b32_e32 v55, s8
	v_pk_mul_f32 v[50:51], v[18:19], v[120:121] op_sel_hi:[1,0]
	v_pk_mul_f32 v[52:53], v[38:39], v[142:143] op_sel_hi:[1,0]
	v_mad_u32_u24 v55, v182, s20, v55
	s_add_u32 s20, s6, s22
	v_pk_fma_f32 v[122:123], v[18:19], v[118:119], v[50:51] op_sel:[1,0,0] op_sel_hi:[0,0,1]
	v_pk_fma_f32 v[50:51], v[18:19], v[118:119], v[50:51] op_sel:[1,0,0] op_sel_hi:[0,0,1] neg_lo:[0,0,1] neg_hi:[0,0,1]
	v_pk_fma_f32 v[146:147], v[38:39], v[138:139], v[52:53] op_sel:[1,0,0] op_sel_hi:[0,0,1]
	v_pk_fma_f32 v[52:53], v[38:39], v[138:139], v[52:53] op_sel:[1,0,0] op_sel_hi:[0,0,1] neg_lo:[0,0,1] neg_hi:[0,0,1]
	v_mul_u32_u24_e32 v54, 0x50, v56
	s_addc_u32 s21, s7, 0
	v_mov_b32_e32 v124, v122
	v_mov_b32_e32 v125, v51
	v_mov_b32_e32 v148, v146
	v_mov_b32_e32 v149, v53
	v_mov_b32_e32 v150, v16
	v_mov_b32_e32 v151, v16
	v_xor_b32_e32 v16, 0x80000000, v17
	v_add_u32_e32 v103, s8, v48
	v_mov_b32_e32 v152, v36
	v_mov_b32_e32 v153, v36
	v_xor_b32_e32 v36, 0x80000000, v37
	v_lshl_add_u64 v[154:155], s[20:21], 0, v[46:47]
	v_mov_b32_e32 v156, v53
	v_mov_b32_e32 v157, v53
	v_pk_mov_b32 v[158:159], v[52:53], v[146:147] op_sel:[1,0]
	v_mov_b32_e32 v160, v51
	v_mov_b32_e32 v161, v51
	v_pk_mov_b32 v[162:163], v[50:51], v[122:123] op_sel:[1,0]
	v_mov_b32_e32 v123, v122
	v_mov_b32_e32 v147, v146
	v_lshl_add_u64 v[164:165], s[2:3], 0, v[48:49]
	v_lshl_or_b32 v166, s5, 6, v182
	s_and_b32 s3, s4, 0xffffffc0
	v_add_u32_e32 v104, s8, v45
	v_add_u32_e32 v109, s8, v54
	v_add_u32_e32 v110, v55, v44
	s_mov_b32 s21, 0x3e6d3388
	s_mov_b32 s2, 0x3f07dc22
	s_mov_b32 s4, 0xbf3a00e3
	s_mov_b32 s8, 0x3f35f0e3
	s_mov_b32 s20, 0xbe11a98e
	s_mov_b32 s22, 0x3e027906
	v_mov_b32_e32 v113, 0x600
	s_branch .LBB0_756

; __device__ __forceinline__ void s5_out_phase(LAS unsigned char* lds, const bf16_t* UZ, const unsigned char* ws, const float* dskip, bf16_t* YG) {
;     ...
;     for (int slot = gw >> 6; slot < 256; slot += sstep) {
;         const int b = slot >> 6, tt = slot & 63, rowbase = b * SEQ + 64 * tt;
;         bf16x4 Uf[4];
; #pragma unroll
;         for (int m = 0; m < 4; ++m) Uf[m] = Un[m];
;         const f32x2 cF_ = s5_carry(rp[0], rq[0], ap[0], 4 + tt), cB_ = s5_carry(rp[1], rq[1], ap[1], 4 + 63 - tt);
;         float xfr = cF_.x, xfi = cF_.y, xbr = cB_.x, xbi = cB_.y;
;         if (slot + sstep < 256) { const int ns = slot + sstep, nb = ns >> 6, ntt = ns & 63;
;             load_uf(Un, UZ, nb * SEQ + 64 * ntt, g, lane);
;             S5_LOADRAW(nb, ntt); }
.LBB0_760:
	s_add_i32 s5, s5, s23
	s_cmp_gt_i32 s5, s101
	s_cselect_b64 s[24:25], -1, 0
	s_and_b64 vcc, exec, s[24:25]
	s_waitcnt vmcnt(11)
	v_mov_b64_e32 v[180:181], v[116:117]
	s_waitcnt vmcnt(10)
	v_mov_b64_e32 v[178:179], v[168:169]
	s_waitcnt vmcnt(9)
	v_mov_b64_e32 v[176:177], v[170:171]
	s_waitcnt vmcnt(1)
	v_mov_b64_e32 v[174:175], v[172:173]
	s_cbranch_vccnz .LBB0_755
	s_ashr_i32 s36, s5, 6
	s_and_b32 s37, s5, 63
	s_lshl_b32 s38, s36, 12
	s_lshl_b32 s39, s37, 6
	s_or_b32 s38, s38, s39
	v_or_b32_e32 v48, s38, v182
	s_lshl_b32 s36, s36, 7
	v_ashrrev_i32_e32 v49, 31, v48
	s_or_b32 s39, s36, s9
	v_lshlrev_b64 v[50:51], 12, v[48:49]
	v_or_b32_e32 v52, 16, v48
	v_or_b32_e32 v54, 32, v48
	v_or_b32_e32 v48, 48, v48
	s_sub_i32 s38, 0x43, s37
	s_add_i32 s37, s37, 4
	s_mul_i32 s36, s39, 0x44
	v_ashrrev_i32_e32 v49, 31, v48
	s_mul_hi_i32 s40, s39, 0x44
	s_add_u32 s36, s36, s37
	v_ashrrev_i32_e32 v53, 31, v52
	v_ashrrev_i32_e32 v55, 31, v54
	v_lshlrev_b64 v[48:49], 12, v[48:49]
	s_addc_u32 s37, s40, 0
	v_lshl_add_u64 v[50:51], v[92:93], 0, v[50:51]
	v_lshlrev_b64 v[52:53], 12, v[52:53]
	v_lshlrev_b64 v[54:55], 12, v[54:55]
	v_lshl_add_u64 v[48:49], v[92:93], 0, v[48:49]
	s_lshl_b64 s[36:37], s[36:37], 9
	v_lshl_add_u64 v[52:53], v[92:93], 0, v[52:53]
	v_lshl_add_u64 v[54:55], v[92:93], 0, v[54:55]
	global_load_dwordx2 v[174:175], v[50:51], off
	global_load_dwordx2 v[176:177], v[52:53], off
	global_load_dwordx2 v[178:179], v[54:55], off
	global_load_dwordx2 v[180:181], v[48:49], off
	v_lshl_add_u64 v[48:49], v[94:95], 0, s[36:37]
	v_mad_i64_i32 v[50:51], s[36:37], s39, v113, v[164:165]
	s_or_b32 s39, s39, 64
	s_mul_i32 s36, s39, 0x44
	s_mul_hi_i32 s37, s39, 0x44
	s_add_u32 s36, s36, s38
	s_addc_u32 s37, s37, 0
	s_lshl_b64 s[36:37], s[36:37], 9
	global_load_dword v100, v[48:49], off
	global_load_dword v101, v[48:49], off offset:256
	global_load_dword v98, v[50:51], off
	global_load_dword v99, v[50:51], off offset:256
	global_load_dword v96, v[50:51], off offset:512
	global_load_dword v97, v[50:51], off offset:768
	global_load_dword v183, v[50:51], off offset:1024
	global_load_dword v184, v[50:51], off offset:1280
	v_lshl_add_u64 v[48:49], v[94:95], 0, s[36:37]
	v_mad_i64_i32 v[50:51], s[36:37], s39, v113, v[164:165]
	global_load_dword v106, v[48:49], off
	global_load_dword v107, v[48:49], off offset:256
	global_load_dword v144, v[50:51], off
	global_load_dword v145, v[50:51], off offset:256
	global_load_dword v140, v[50:51], off offset:512
	global_load_dword v141, v[50:51], off offset:768
	global_load_dword v185, v[50:51], off offset:1024
	global_load_dword v186, v[50:51], off offset:1280
	s_branch .LBB0_755
.Lp9_exit:
	s_cmp_lg_u32 s100, 0
	s_cbranch_scc1 .LBB0_762
	v_readfirstlane_b32 s2, v192
	s_lshr_b32 s8, s2, 6
	s_cmp_gt_u32 s8, 3
	s_cbranch_scc1 .LBB0_762
	s_lshl_b32 s2, s12, 3
	s_add_i32 s24, s8, s2
	s_addk_i32 s24, 0x3804
	s_mov_b64 s[20:21], s[96:97]
	s_mov_b32 s100, 1
	s_movk_i32 s101, 0xff
	s_branch .Lp9_entry
